# mixer C: first 7 P.V fragment reads of each MFMA half issued before the preceding workgroup barrier (slot published one barrier earlier); 7-deep read pipeline; max3 tree
# speedup vs baseline: 1.0094x; 1.0052x over previous
.LBB0_560:
	v_add_u32_e32 v0, s2, v219
	ds_read_b128 v[222:225], v0
	ds_read_b128 v[226:229], v0 offset:4608
	ds_read_b128 v[230:233], v0 offset:32
	ds_read_b128 v[234:237], v0 offset:4640
	ds_read_b128 v[238:241], v0 offset:64
	ds_read_b128 v[242:245], v0 offset:4672
	ds_read_b128 v[246:249], v0 offset:96
	s_andn2_b64 vcc, exec, s[96:97]
	s_waitcnt lgkmcnt(6)
	v_mfma_f32_32x32x16_bf16 v[2:17], v[222:225], v[112:115], v[2:17]
	ds_read_b128 v[222:225], v0 offset:4704
	s_waitcnt lgkmcnt(6)
	v_mfma_f32_32x32x16_bf16 v[18:33], v[226:229], v[112:115], v[18:33]
	s_waitcnt lgkmcnt(5)
	v_mfma_f32_32x32x16_bf16 v[2:17], v[230:233], v[116:119], v[2:17]
	s_waitcnt lgkmcnt(4)
	v_mfma_f32_32x32x16_bf16 v[18:33], v[234:237], v[116:119], v[18:33]
	s_waitcnt lgkmcnt(3)
	v_mfma_f32_32x32x16_bf16 v[2:17], v[238:241], v[120:123], v[2:17]
	s_waitcnt lgkmcnt(2)
	v_mfma_f32_32x32x16_bf16 v[18:33], v[242:245], v[120:123], v[18:33]
	s_waitcnt lgkmcnt(1)
	v_mfma_f32_32x32x16_bf16 v[2:17], v[246:249], v[124:127], v[2:17]
	v_cndmask_b32_e64 v0, 0, 1, s[96:97]
	v_cmp_ne_u32_e64 s[4:5], 1, v0
	s_waitcnt lgkmcnt(0)
	v_mfma_f32_32x32x16_bf16 v[18:33], v[222:225], v[124:127], v[18:33]
	s_cbranch_vccnz .LBB0_562
	s_bitcmp1_b32 s43, 0
	s_cselect_b32 s2, 0, 0x4800
	v_add_u32_e32 v0, s2, v218
	s_waitcnt vmcnt(3)
	ds_write_b128 v0, v[144:147]
	s_waitcnt vmcnt(2)
	ds_write_b128 v0, v[148:151] offset:9216
	v_add_u32_e32 v0, 0xd800, v217
	s_waitcnt vmcnt(1)
	ds_write2_b64 v0, v[152:153], v[154:155] offset1:2
	v_add_u32_e32 v0, 0xf800, v217
	s_waitcnt vmcnt(0)
	ds_write2_b64 v0, v[156:157], v[158:159] offset0:128 offset1:130

; #define C3_BAR() asm volatile("s_waitcnt lgkmcnt(0)\n\ts_barrier" ::: "memory")
; __device__ __forceinline__ void attn_C5(const Ctx& a, LAS unsigned char* lds, int wave_s) {
;     ...
;             for (int t = t_lo; t < TE; ++t) {
;                 C3_BAR();
;                 if (t > t_lo) { const int vsp = vs == 0 ? 2 : vs - 1; C3_PV(vsp); } C3_QK(t);
.LBB0_567:
	s_mul_i32 s32, s2, 0x4800
	s_addk_i32 s32, 0xb800
	s_cmp_lg_u32 s2, 0
	s_cselect_b32 s32, s32, 0x9000
	v_add_u32_e32 v250, s32, v215
	ds_read_b128 v[222:225], v250 offset:36864
	ds_read_b128 v[226:229], v250 offset:36896
	ds_read_b128 v[230:233], v250 offset:36928
	ds_read_b128 v[234:237], v250 offset:36960
	ds_read_b128 v[238:241], v250 offset:41472
	ds_read_b128 v[242:245], v250 offset:41504
	ds_read_b128 v[246:249], v250 offset:41536
	s_waitcnt lgkmcnt(7)
	s_barrier
	s_add_i32 s13, s12, -2
	s_cmp_le_u32 s13, s43
	s_cbranch_scc1 .LBB0_569
	s_mul_i32 s4, s2, 0x4800
	s_addk_i32 s4, 0xb800
	s_cmp_lg_u32 s2, 0
	s_cselect_b32 s4, s4, 0x9000
	v_add_u32_e32 v0, s4, v215
	s_setprio 1
	s_waitcnt lgkmcnt(6)
	v_mfma_f32_32x32x16_bf16 v[64:79], v[222:225], v[80:83], v[64:79]
	ds_read_b128 v[222:225], v250 offset:41568
	s_waitcnt lgkmcnt(6)
	v_mfma_f32_32x32x16_bf16 v[64:79], v[226:229], v[84:87], v[64:79]
	ds_read_b128 v[226:229], v250 offset:46080
	s_waitcnt lgkmcnt(6)
	v_mfma_f32_32x32x16_bf16 v[64:79], v[230:233], v[88:91], v[64:79]
	ds_read_b128 v[230:233], v250 offset:46112
	s_waitcnt lgkmcnt(6)
	v_mfma_f32_32x32x16_bf16 v[64:79], v[234:237], v[92:95], v[64:79]
	ds_read_b128 v[234:237], v250 offset:46144
	s_waitcnt lgkmcnt(6)
	v_mfma_f32_32x32x16_bf16 v[48:63], v[238:241], v[80:83], v[48:63]
	ds_read_b128 v[238:241], v250 offset:46176
	s_waitcnt lgkmcnt(6)
	v_mfma_f32_32x32x16_bf16 v[48:63], v[242:245], v[84:87], v[48:63]
	ds_read_b128 v[242:245], v250 offset:50688
	s_waitcnt lgkmcnt(6)
	v_mfma_f32_32x32x16_bf16 v[48:63], v[246:249], v[88:91], v[48:63]
	ds_read_b128 v[246:249], v250 offset:50720
	s_waitcnt lgkmcnt(6)
	v_mfma_f32_32x32x16_bf16 v[48:63], v[222:225], v[92:95], v[48:63]
	ds_read_b128 v[222:225], v250 offset:50752
	s_waitcnt lgkmcnt(6)
	v_mfma_f32_32x32x16_bf16 v[32:47], v[226:229], v[80:83], v[32:47]
	ds_read_b128 v[226:229], v250 offset:50784
	s_waitcnt lgkmcnt(6)
	v_mfma_f32_32x32x16_bf16 v[32:47], v[230:233], v[84:87], v[32:47]
	s_waitcnt lgkmcnt(5)
	v_mfma_f32_32x32x16_bf16 v[32:47], v[234:237], v[88:91], v[32:47]
	s_waitcnt lgkmcnt(4)
	v_mfma_f32_32x32x16_bf16 v[32:47], v[238:241], v[92:95], v[32:47]
	s_waitcnt lgkmcnt(3)
	v_mfma_f32_32x32x16_bf16 v[16:31], v[242:245], v[80:83], v[16:31]
	s_waitcnt lgkmcnt(2)
	v_mfma_f32_32x32x16_bf16 v[16:31], v[246:249], v[84:87], v[16:31]
	s_waitcnt lgkmcnt(1)
	v_mfma_f32_32x32x16_bf16 v[16:31], v[222:225], v[88:91], v[16:31]
	s_waitcnt lgkmcnt(0)
	v_mfma_f32_32x32x16_bf16 v[16:31], v[226:229], v[92:95], v[16:31]
	s_setprio 0

.LBB0_576:
	s_bitcmp1_b32 s13, 0
	s_cselect_b32 s4, 0x4800, 0
	v_add_u32_e32 v0, s4, v219
	ds_read_b128 v[222:225], v0
	ds_read_b128 v[226:229], v0 offset:4608
	ds_read_b128 v[230:233], v0 offset:32
	ds_read_b128 v[234:237], v0 offset:4640
	ds_read_b128 v[238:241], v0 offset:64
	ds_read_b128 v[242:245], v0 offset:4672
	ds_read_b128 v[246:249], v0 offset:96
	s_add_i32 s4, s2, 1
	s_cmp_lg_u32 s2, 2
	s_cselect_b32 s2, s4, 0
	s_cmp_ge_i32 s13, s42
	s_waitcnt lgkmcnt(6)
	v_mfma_f32_32x32x16_bf16 v[80:95], v[222:225], v[112:115], v[80:95]
	ds_read_b128 v[222:225], v0 offset:4704
	s_waitcnt lgkmcnt(6)
	v_mfma_f32_32x32x16_bf16 v[96:111], v[226:229], v[112:115], v[96:111]
	s_waitcnt lgkmcnt(5)
	v_mfma_f32_32x32x16_bf16 v[80:95], v[230:233], v[116:119], v[80:95]
	s_waitcnt lgkmcnt(4)
	v_mfma_f32_32x32x16_bf16 v[96:111], v[234:237], v[116:119], v[96:111]
	s_waitcnt lgkmcnt(3)
	v_mfma_f32_32x32x16_bf16 v[80:95], v[238:241], v[120:123], v[80:95]
	s_waitcnt lgkmcnt(2)
	v_mfma_f32_32x32x16_bf16 v[96:111], v[242:245], v[120:123], v[96:111]
	s_waitcnt lgkmcnt(1)
	v_mfma_f32_32x32x16_bf16 v[80:95], v[246:249], v[124:127], v[80:95]
	s_waitcnt lgkmcnt(0)
	v_mfma_f32_32x32x16_bf16 v[96:111], v[222:225], v[124:127], v[96:111]
	s_cbranch_scc1 .LBB0_578
	s_bitcmp1_b32 s12, 0
	s_cselect_b32 s4, 0, 0x4800
	v_add_u32_e32 v0, s4, v218
	s_mul_i32 s4, s2, 0x4800
	s_waitcnt vmcnt(3)
	ds_write_b128 v0, v[160:163]
	s_waitcnt vmcnt(2)
	ds_write_b128 v0, v[164:167] offset:9216
	v_add_u32_e32 v0, s4, v217
	v_add_u32_e32 v2, 0x9000, v0
	v_add_u32_e32 v0, 0xb000, v0
	s_waitcnt vmcnt(1)
	ds_write2_b64 v2, v[168:169], v[170:171] offset1:2
	s_waitcnt vmcnt(0)
	ds_write2_b64 v0, v[172:173], v[174:175] offset0:128 offset1:130

; #define C3_BAR() asm volatile("s_waitcnt lgkmcnt(0)\n\ts_barrier" ::: "memory")
; __device__ __forceinline__ void attn_C5(const Ctx& a, LAS unsigned char* lds, int wave_s) {
;     ...
;             C3_BAR();
;             { const int vsp = vs == 0 ? 2 : vs - 1; C3_PV(vsp); }
.LBB0_585:
	s_mul_i32 s4, s2, 0x4800
	s_waitcnt lgkmcnt(0)
	s_barrier
	s_addk_i32 s4, 0xb800
	s_cmp_lg_u32 s2, 0
	s_cselect_b32 s2, s4, 0x9000
	v_add_u32_e32 v0, s2, v215
	s_setprio 1
	ds_read_b128 v[222:225], v0 offset:36864
	ds_read_b128 v[226:229], v0 offset:36896
	ds_read_b128 v[230:233], v0 offset:36928
	ds_read_b128 v[234:237], v0 offset:36960
	ds_read_b128 v[238:241], v0 offset:41472
	ds_read_b128 v[242:245], v0 offset:41504
	ds_read_b128 v[246:249], v0 offset:41536
	s_waitcnt lgkmcnt(6)
	v_mfma_f32_32x32x16_bf16 v[64:79], v[222:225], v[96:99], v[64:79]
	ds_read_b128 v[222:225], v0 offset:41568
	s_waitcnt lgkmcnt(6)
	v_mfma_f32_32x32x16_bf16 v[64:79], v[226:229], v[6:9], v[64:79]
	ds_read_b128 v[226:229], v0 offset:46080
	s_waitcnt lgkmcnt(6)
	v_mfma_f32_32x32x16_bf16 v[64:79], v[230:233], v[10:13], v[64:79]
	ds_read_b128 v[230:233], v0 offset:46112
	s_waitcnt lgkmcnt(6)
	v_mfma_f32_32x32x16_bf16 v[64:79], v[234:237], v[2:5], v[64:79]
	ds_read_b128 v[234:237], v0 offset:46144
	s_waitcnt lgkmcnt(6)
	v_mfma_f32_32x32x16_bf16 v[48:63], v[238:241], v[96:99], v[48:63]
	ds_read_b128 v[238:241], v0 offset:46176
	s_waitcnt lgkmcnt(6)
	v_mfma_f32_32x32x16_bf16 v[48:63], v[242:245], v[6:9], v[48:63]
	ds_read_b128 v[242:245], v0 offset:50688
	s_waitcnt lgkmcnt(6)
	v_mfma_f32_32x32x16_bf16 v[48:63], v[246:249], v[10:13], v[48:63]
	ds_read_b128 v[246:249], v0 offset:50720
	s_waitcnt lgkmcnt(6)
	v_mfma_f32_32x32x16_bf16 v[48:63], v[222:225], v[2:5], v[48:63]
	ds_read_b128 v[222:225], v0 offset:50752
	s_waitcnt lgkmcnt(6)
	v_mfma_f32_32x32x16_bf16 v[32:47], v[226:229], v[96:99], v[32:47]
	ds_read_b128 v[226:229], v0 offset:50784
	s_waitcnt lgkmcnt(6)
	v_mfma_f32_32x32x16_bf16 v[32:47], v[230:233], v[6:9], v[32:47]
	s_waitcnt lgkmcnt(5)
	v_mfma_f32_32x32x16_bf16 v[32:47], v[234:237], v[10:13], v[32:47]
	s_waitcnt lgkmcnt(4)
	v_mfma_f32_32x32x16_bf16 v[32:47], v[238:241], v[2:5], v[32:47]
	s_waitcnt lgkmcnt(3)
	v_mfma_f32_32x32x16_bf16 v[16:31], v[242:245], v[96:99], v[16:31]
	s_waitcnt lgkmcnt(2)
	v_mfma_f32_32x32x16_bf16 v[16:31], v[246:249], v[6:9], v[16:31]
	s_waitcnt lgkmcnt(1)
	v_mfma_f32_32x32x16_bf16 v[16:31], v[222:225], v[10:13], v[16:31]
	s_waitcnt lgkmcnt(0)
	v_mfma_f32_32x32x16_bf16 v[16:31], v[226:229], v[2:5], v[16:31]
	s_setprio 0
	s_mov_b64 s[4:5], 0

.LBB0_594:
	v_add_u32_e32 v0, s24, v214
	ds_read_b128 v[222:225], v0
	ds_read_b128 v[226:229], v0 offset:4608
	ds_read_b128 v[230:233], v0 offset:32
	ds_read_b128 v[234:237], v0 offset:4640
	ds_read_b128 v[238:241], v0 offset:64
	ds_read_b128 v[242:245], v0 offset:4672
	ds_read_b128 v[246:249], v0 offset:96
	s_cmp_gt_i32 s43, s42
	s_waitcnt lgkmcnt(6)
	v_mfma_f32_32x32x16_bf16 v[2:17], v[222:225], v[112:115], v[2:17]
	ds_read_b128 v[222:225], v0 offset:4704
	s_waitcnt lgkmcnt(6)
	v_mfma_f32_32x32x16_bf16 v[18:33], v[226:229], v[112:115], v[18:33]
	s_waitcnt lgkmcnt(5)
	v_mfma_f32_32x32x16_bf16 v[2:17], v[230:233], v[116:119], v[2:17]
	s_waitcnt lgkmcnt(4)
	v_mfma_f32_32x32x16_bf16 v[18:33], v[234:237], v[116:119], v[18:33]
	s_waitcnt lgkmcnt(3)
	v_mfma_f32_32x32x16_bf16 v[2:17], v[238:241], v[120:123], v[2:17]
	s_waitcnt lgkmcnt(2)
	v_mfma_f32_32x32x16_bf16 v[18:33], v[242:245], v[120:123], v[18:33]
	s_waitcnt lgkmcnt(1)
	v_mfma_f32_32x32x16_bf16 v[2:17], v[246:249], v[124:127], v[2:17]
	s_waitcnt lgkmcnt(0)
	v_mfma_f32_32x32x16_bf16 v[18:33], v[222:225], v[124:127], v[18:33]
	s_cbranch_scc1 .LBB0_627
	s_nop 10
	v_max_f32_e32 v0, v19, v19
	v_max_f32_e32 v34, v3, v3
	v_max_f32_e32 v0, v34, v0
	v_max_f32_e32 v34, v20, v20
	v_max_f32_e32 v35, v4, v4
	v_max_f32_e32 v34, v35, v34
	v_max_f32_e32 v35, v21, v21
	v_max_f32_e32 v36, v5, v5
	v_max3_f32 v0, v2, v18, v0
	v_max_f32_e32 v35, v36, v35
	v_max3_f32 v0, v0, v34, v35
	v_max_f32_e32 v34, v22, v22
	v_max_f32_e32 v35, v6, v6
	v_max_f32_e32 v34, v35, v34
	v_max_f32_e32 v35, v23, v23
	v_max_f32_e32 v36, v7, v7
	v_max_f32_e32 v35, v36, v35
	v_max3_f32 v0, v0, v34, v35
	v_max_f32_e32 v34, v24, v24
	v_max_f32_e32 v35, v8, v8
	v_max_f32_e32 v34, v35, v34
	v_max_f32_e32 v35, v25, v25
	v_max_f32_e32 v36, v9, v9
	v_max_f32_e32 v35, v36, v35
	v_max3_f32 v0, v0, v34, v35
	v_max_f32_e32 v34, v26, v26
	v_max_f32_e32 v35, v10, v10
	v_max_f32_e32 v34, v35, v34
	v_max_f32_e32 v35, v27, v27
	v_max_f32_e32 v36, v11, v11
	v_max_f32_e32 v35, v36, v35
	v_max3_f32 v0, v0, v34, v35
	v_max_f32_e32 v34, v28, v28
	v_max_f32_e32 v35, v12, v12
	v_max_f32_e32 v34, v35, v34
	v_max_f32_e32 v35, v29, v29
	v_max_f32_e32 v36, v13, v13
	v_max_f32_e32 v35, v36, v35
	v_max3_f32 v0, v0, v34, v35
	v_max_f32_e32 v34, v30, v30
	v_max_f32_e32 v35, v14, v14
	v_max_f32_e32 v34, v35, v34
	v_max_f32_e32 v35, v31, v31
	v_max_f32_e32 v36, v15, v15
	v_max_f32_e32 v35, v36, v35
	v_max3_f32 v0, v0, v34, v35
	v_max_f32_e32 v34, v32, v32
	v_max_f32_e32 v35, v16, v16
	v_max_f32_e32 v34, v35, v34
	v_max_f32_e32 v35, v33, v33
	v_max_f32_e32 v36, v17, v17
	v_max_f32_e32 v35, v36, v35
	v_max3_f32 v0, v0, v34, v35
	v_mov_b32_e32 v34, v0
	s_nop 1
	v_permlane32_swap_b32_e32 v0, v34
	v_max_f32_e32 v34, v34, v34
	v_max_f32_e32 v0, v0, v0
	v_max_f32_e32 v35, v0, v34
	v_sub_f32_e32 v2, v2, v35
	v_exp_f32_e32 v80, v2
	v_sub_f32_e32 v0, v18, v35
	v_exp_f32_e32 v96, v0
	v_sub_f32_e32 v3, v3, v35
	v_add_f32_e32 v0, 0, v80
	v_exp_f32_e32 v81, v3
	s_waitcnt lgkmcnt(0)
	s_barrier
	v_sub_f32_e32 v18, v19, v35
	v_exp_f32_e32 v97, v18
	v_add_f32_e32 v0, v0, v96
	v_sub_f32_e32 v4, v4, v35
	v_exp_f32_e32 v82, v4
	v_add_f32_e32 v0, v0, v81
	v_sub_f32_e32 v19, v20, v35
	v_exp_f32_e32 v98, v19
	v_add_f32_e32 v0, v0, v97
	v_sub_f32_e32 v5, v5, v35
	v_exp_f32_e32 v83, v5
	v_add_f32_e32 v0, v0, v82
	v_sub_f32_e32 v20, v21, v35
	v_exp_f32_e32 v99, v20
	v_add_f32_e32 v0, v98, v0
	v_sub_f32_e32 v6, v6, v35
	v_exp_f32_e32 v84, v6
	v_add_f32_e32 v0, v83, v0
	v_sub_f32_e32 v21, v22, v35
	v_exp_f32_e32 v100, v21
	v_add_f32_e32 v0, v99, v0
	v_sub_f32_e32 v7, v7, v35
	v_exp_f32_e32 v85, v7
	v_add_f32_e32 v0, v84, v0
	v_sub_f32_e32 v22, v23, v35
	v_exp_f32_e32 v101, v22
	v_add_f32_e32 v0, v100, v0
	v_sub_f32_e32 v8, v8, v35
	v_exp_f32_e32 v86, v8
	v_add_f32_e32 v0, v85, v0
	v_sub_f32_e32 v23, v24, v35
	v_exp_f32_e32 v102, v23
	v_add_f32_e32 v0, v101, v0
	v_sub_f32_e32 v9, v9, v35
	v_exp_f32_e32 v87, v9
	v_add_f32_e32 v0, v86, v0
	v_sub_f32_e32 v24, v25, v35
	v_exp_f32_e32 v103, v24
	v_add_f32_e32 v0, v102, v0
	v_sub_f32_e32 v10, v10, v35
	v_exp_f32_e32 v88, v10
	v_add_f32_e32 v0, v87, v0
	v_sub_f32_e32 v25, v26, v35
	v_exp_f32_e32 v104, v25
	v_add_f32_e32 v0, v103, v0
	v_sub_f32_e32 v11, v11, v35
	v_exp_f32_e32 v89, v11
	v_add_f32_e32 v0, v88, v0
	v_sub_f32_e32 v26, v27, v35
	v_exp_f32_e32 v105, v26
	v_add_f32_e32 v0, v104, v0
	v_sub_f32_e32 v12, v12, v35
	v_exp_f32_e32 v90, v12
	v_add_f32_e32 v0, v89, v0
	v_sub_f32_e32 v27, v28, v35
	v_exp_f32_e32 v106, v27
	v_add_f32_e32 v0, v105, v0
	v_sub_f32_e32 v13, v13, v35
	v_exp_f32_e32 v91, v13
	v_add_f32_e32 v0, v90, v0
	v_sub_f32_e32 v28, v29, v35
	v_exp_f32_e32 v107, v28
	v_add_f32_e32 v0, v106, v0
	v_sub_f32_e32 v14, v14, v35
	v_exp_f32_e32 v92, v14
	v_add_f32_e32 v0, v91, v0
	v_sub_f32_e32 v29, v30, v35
	v_exp_f32_e32 v108, v29
	v_add_f32_e32 v0, v107, v0
	v_sub_f32_e32 v15, v15, v35
	v_exp_f32_e32 v93, v15
	v_add_f32_e32 v0, v92, v0
	v_sub_f32_e32 v30, v31, v35
	v_exp_f32_e32 v109, v30
	v_add_f32_e32 v0, v108, v0
	v_sub_f32_e32 v2, v16, v35
	v_exp_f32_e32 v94, v2
	v_add_f32_e32 v0, v93, v0
	v_sub_f32_e32 v31, v32, v35
	v_exp_f32_e32 v110, v31
	v_add_f32_e32 v0, v109, v0
	v_sub_f32_e32 v16, v17, v35
	v_exp_f32_e32 v95, v16
	v_add_f32_e32 v0, v94, v0
	v_sub_f32_e32 v32, v33, v35
	v_exp_f32_e32 v111, v32
	v_add_f32_e32 v0, v110, v0
	s_andn2_b64 vcc, exec, s[96:97]
	v_add_f32_e32 v0, v95, v0
	s_add_i32 s2, s43, 1
	v_add_f32_e32 v34, v111, v0
	v_cndmask_b32_e64 v0, 0, 1, s[96:97]
	v_cmp_ne_u32_e64 s[4:5], 1, v0
	s_cbranch_vccnz .LBB0_597
	s_bitcmp1_b32 s2, 0
	s_cselect_b32 s8, 0x4800, 0
	v_add_u32_e32 v0, s8, v218
	s_waitcnt vmcnt(3)
	ds_write_b128 v0, v[144:147]
	s_waitcnt vmcnt(2)
	ds_write_b128 v0, v[148:151] offset:9216
	v_add_u32_e32 v0, 0xd800, v217
	s_waitcnt vmcnt(1)
	ds_write2_b64 v0, v[152:153], v[154:155] offset1:2
	v_add_u32_e32 v0, 0xf800, v217
	s_waitcnt vmcnt(0)
	ds_write2_b64 v0, v[156:157], v[158:159] offset0:128 offset1:130

.LBB0_599:
	s_or_b32 s8, s38, 31
	v_pk_add_f32 v[194:195], v[34:35], 0 op_sel_hi:[1,0]
	v_cvt_pk_bf16_f32 v128, v80, v81
	v_cvt_pk_bf16_f32 v129, v82, v83
	v_cvt_pk_bf16_f32 v130, v84, v85
	v_cvt_pk_bf16_f32 v131, v86, v87
	v_cvt_pk_bf16_f32 v132, v88, v89
	v_cvt_pk_bf16_f32 v133, v90, v91
	v_cvt_pk_bf16_f32 v134, v92, v93
	v_cvt_pk_bf16_f32 v135, v94, v95
	v_cvt_pk_bf16_f32 v136, v96, v97
	v_cvt_pk_bf16_f32 v137, v98, v99
	v_cvt_pk_bf16_f32 v138, v100, v101
	v_cvt_pk_bf16_f32 v139, v102, v103
	v_cvt_pk_bf16_f32 v140, v104, v105
	v_cvt_pk_bf16_f32 v141, v106, v107
	v_cvt_pk_bf16_f32 v142, v108, v109
	v_cvt_pk_bf16_f32 v143, v110, v111
	s_setprio 1
	ds_read_b128 v[222:225], v215 offset:36864
	ds_read_b128 v[226:229], v215 offset:36896
	ds_read_b128 v[230:233], v215 offset:36928
	ds_read_b128 v[234:237], v215 offset:36960
	ds_read_b128 v[238:241], v215 offset:41472
	ds_read_b128 v[242:245], v215 offset:41504
	ds_read_b128 v[246:249], v215 offset:41536
	s_waitcnt lgkmcnt(6)
	v_mfma_f32_32x32x16_bf16 v[64:79], v[222:225], v[128:131], 0
	ds_read_b128 v[222:225], v215 offset:41568
	s_waitcnt lgkmcnt(6)
	v_mfma_f32_32x32x16_bf16 v[64:79], v[226:229], v[132:135], v[64:79]
	ds_read_b128 v[226:229], v215 offset:46080
	s_waitcnt lgkmcnt(6)
	v_mfma_f32_32x32x16_bf16 v[64:79], v[230:233], v[136:139], v[64:79]
	ds_read_b128 v[230:233], v215 offset:46112
	s_waitcnt lgkmcnt(6)
	v_mfma_f32_32x32x16_bf16 v[64:79], v[234:237], v[140:143], v[64:79]
	ds_read_b128 v[234:237], v215 offset:46144
	s_waitcnt lgkmcnt(6)
	v_mfma_f32_32x32x16_bf16 v[48:63], v[238:241], v[128:131], 0
	ds_read_b128 v[238:241], v215 offset:46176
	s_waitcnt lgkmcnt(6)
	v_mfma_f32_32x32x16_bf16 v[48:63], v[242:245], v[132:135], v[48:63]
	ds_read_b128 v[242:245], v215 offset:50688
	s_waitcnt lgkmcnt(6)
	v_mfma_f32_32x32x16_bf16 v[48:63], v[246:249], v[136:139], v[48:63]
	ds_read_b128 v[246:249], v215 offset:50720
	s_waitcnt lgkmcnt(6)
	v_mfma_f32_32x32x16_bf16 v[48:63], v[222:225], v[140:143], v[48:63]
	ds_read_b128 v[222:225], v215 offset:50752
	s_waitcnt lgkmcnt(6)
	v_mfma_f32_32x32x16_bf16 v[32:47], v[226:229], v[128:131], 0
	ds_read_b128 v[226:229], v215 offset:50784
	s_waitcnt lgkmcnt(6)
	v_mfma_f32_32x32x16_bf16 v[32:47], v[230:233], v[132:135], v[32:47]
	s_waitcnt lgkmcnt(5)
	v_mfma_f32_32x32x16_bf16 v[32:47], v[234:237], v[136:139], v[32:47]
	s_waitcnt lgkmcnt(4)
	v_mfma_f32_32x32x16_bf16 v[32:47], v[238:241], v[140:143], v[32:47]
	s_waitcnt lgkmcnt(3)
	v_mfma_f32_32x32x16_bf16 v[16:31], v[242:245], v[128:131], 0
	s_waitcnt lgkmcnt(2)
	v_mfma_f32_32x32x16_bf16 v[16:31], v[246:249], v[132:135], v[16:31]
	s_waitcnt lgkmcnt(1)
	v_mfma_f32_32x32x16_bf16 v[16:31], v[222:225], v[136:139], v[16:31]
	s_waitcnt lgkmcnt(0)
	v_mfma_f32_32x32x16_bf16 v[16:31], v[226:229], v[140:143], v[16:31]
	s_setprio 0
	s_and_b64 vcc, exec, s[4:5]
	s_cbranch_vccnz .LBB0_608
	s_lshl_b32 s10, s2, 6
	v_cvt_f32_u32_e32 v2, s10
	s_add_i32 s12, s10, 64
	v_mov_b32_e32 v0, v191
	s_cmp_gt_u32 s12, s38
	v_sub_f32_e32 v2, v221, v2
	s_mov_b64 s[24:25], -1
	s_cbranch_scc1 .LBB0_602
	v_fma_f32 v111, v2, -v0, -v195
	v_fma_f32 v80, 0, v0, v111
	v_fmamk_f32 v96, v0, 0x42000000, v111
	v_add_f32_e32 v81, v0, v111
	v_fmamk_f32 v97, v0, 0x42040000, v111
	v_fma_f32 v82, 2.0, v0, v111
	v_fmamk_f32 v98, v0, 0x42080000, v111
	v_fmamk_f32 v83, v0, 0x40400000, v111
	v_fmamk_f32 v99, v0, 0x420c0000, v111
	v_fmamk_f32 v84, v0, 0x41000000, v111
	v_fmamk_f32 v100, v0, 0x42200000, v111
	v_fmamk_f32 v85, v0, 0x41100000, v111
	v_fmamk_f32 v101, v0, 0x42240000, v111
	v_fmamk_f32 v86, v0, 0x41200000, v111
	v_fmamk_f32 v102, v0, 0x42280000, v111
	v_fmamk_f32 v87, v0, 0x41300000, v111
	v_fmamk_f32 v103, v0, 0x422c0000, v111
	v_fmamk_f32 v88, v0, 0x41800000, v111
	v_fmamk_f32 v104, v0, 0x42400000, v111
	v_fmamk_f32 v89, v0, 0x41880000, v111
	v_fmamk_f32 v105, v0, 0x42440000, v111
	v_fmamk_f32 v90, v0, 0x41900000, v111
	v_fmamk_f32 v106, v0, 0x42480000, v111
	v_fmamk_f32 v91, v0, 0x41980000, v111
	v_fmamk_f32 v107, v0, 0x424c0000, v111
	v_fmamk_f32 v92, v0, 0x41c00000, v111
	v_fmamk_f32 v108, v0, 0x42600000, v111
	v_fmamk_f32 v93, v0, 0x41c80000, v111
	v_fmamk_f32 v109, v0, 0x42640000, v111
	v_fmamk_f32 v94, v0, 0x41d00000, v111
	v_fmamk_f32 v110, v0, 0x42680000, v111
	v_fmamk_f32 v95, v0, 0x41d80000, v111
	v_fmac_f32_e32 v111, 0x426c0000, v0
	s_mov_b64 s[24:25], 0

.LBB0_607:
	s_bitcmp1_b32 s2, 0
	s_cselect_b32 s2, 0x4800, 0
	v_add_u32_e32 v0, s2, v215
	ds_read_b128 v[222:225], v0
	ds_read_b128 v[226:229], v0 offset:4608
	ds_read_b128 v[230:233], v0 offset:32
	ds_read_b128 v[234:237], v0 offset:4640
	ds_read_b128 v[238:241], v0 offset:64
	ds_read_b128 v[242:245], v0 offset:4672
	ds_read_b128 v[246:249], v0 offset:96
	s_waitcnt lgkmcnt(6)
	v_mfma_f32_32x32x16_bf16 v[80:95], v[222:225], v[112:115], v[80:95]
	ds_read_b128 v[222:225], v0 offset:4704
	s_waitcnt lgkmcnt(6)
	v_mfma_f32_32x32x16_bf16 v[96:111], v[226:229], v[112:115], v[96:111]
	s_waitcnt lgkmcnt(5)
	v_mfma_f32_32x32x16_bf16 v[80:95], v[230:233], v[116:119], v[80:95]
	s_waitcnt lgkmcnt(4)
	v_mfma_f32_32x32x16_bf16 v[96:111], v[234:237], v[116:119], v[96:111]
	s_waitcnt lgkmcnt(3)
	v_mfma_f32_32x32x16_bf16 v[80:95], v[238:241], v[120:123], v[80:95]
	s_waitcnt lgkmcnt(2)
	v_mfma_f32_32x32x16_bf16 v[96:111], v[242:245], v[120:123], v[96:111]
	s_waitcnt lgkmcnt(1)
	v_mfma_f32_32x32x16_bf16 v[80:95], v[246:249], v[124:127], v[80:95]
	s_waitcnt lgkmcnt(0)
	v_mfma_f32_32x32x16_bf16 v[96:111], v[222:225], v[124:127], v[96:111]

.LBB0_614:
	s_mul_i32 s32, s13, 0x4800
	v_add_u32_e32 v250, s32, v215
	ds_read_b128 v[222:225], v250 offset:36864
	ds_read_b128 v[226:229], v250 offset:36896
	ds_read_b128 v[230:233], v250 offset:36928
	ds_read_b128 v[234:237], v250 offset:36960
	ds_read_b128 v[238:241], v250 offset:41472
	ds_read_b128 v[242:245], v250 offset:41504
	ds_read_b128 v[246:249], v250 offset:41536
	s_waitcnt lgkmcnt(7)
	s_barrier
	s_add_i32 s18, s43, 3
	s_cmp_gt_i32 s18, s42
	s_cbranch_scc1 .LBB0_616
	s_lshl_b64 s[44:45], s[10:11], 11
	s_add_u32 s44, s27, s44
	s_addc_u32 s45, s39, s45
	s_lshl_b64 s[58:59], s[10:11], 1
	s_add_u32 s62, s40, s58
	v_mov_b32_e32 v4, v213
	v_mov_b32_e32 v0, v212
	s_addc_u32 s63, s41, s59
	v_mov_b32_e32 v5, v1
	s_add_u32 s58, s94, s58
	v_lshl_add_u64 v[6:7], v[0:1], 1, s[44:45]
	v_lshlrev_b64 v[4:5], 1, v[4:5]
	s_addc_u32 s59, s95, s59
	global_load_dwordx4 v[144:147], v[6:7], off
	global_load_dwordx4 v[148:151], v[6:7], off offset:128
	v_lshl_add_u64 v[6:7], s[62:63], 0, v[4:5]
	v_lshl_add_u64 v[4:5], s[58:59], 0, v[4:5]
	global_load_dwordx4 v[152:155], v[6:7], off
	global_load_dwordx4 v[156:159], v[4:5], off
.LBB0_616:
	v_cvt_pk_bf16_f32 v128, v80, v81
	v_cvt_pk_bf16_f32 v129, v82, v83
	v_cvt_pk_bf16_f32 v130, v84, v85
	v_cvt_pk_bf16_f32 v131, v86, v87
	v_cvt_pk_bf16_f32 v132, v88, v89
	v_cvt_pk_bf16_f32 v133, v90, v91
	v_cvt_pk_bf16_f32 v134, v92, v93
	v_cvt_pk_bf16_f32 v135, v94, v95
	v_cvt_pk_bf16_f32 v136, v96, v97
	v_cvt_pk_bf16_f32 v137, v98, v99
	v_cvt_pk_bf16_f32 v138, v100, v101
	v_cvt_pk_bf16_f32 v139, v102, v103
	v_cvt_pk_bf16_f32 v140, v104, v105
	v_cvt_pk_bf16_f32 v141, v106, v107
	v_cvt_pk_bf16_f32 v142, v108, v109
	v_cvt_pk_bf16_f32 v143, v110, v111
	s_mulk_i32 s13, 0x4800
	v_add_u32_e32 v0, s13, v215
	s_setprio 1
	s_waitcnt lgkmcnt(6)
	v_mfma_f32_32x32x16_bf16 v[64:79], v[222:225], v[128:131], v[64:79]
	ds_read_b128 v[222:225], v250 offset:41568
	s_waitcnt lgkmcnt(6)
	v_mfma_f32_32x32x16_bf16 v[64:79], v[226:229], v[132:135], v[64:79]
	ds_read_b128 v[226:229], v250 offset:46080
	s_waitcnt lgkmcnt(6)
	v_mfma_f32_32x32x16_bf16 v[64:79], v[230:233], v[136:139], v[64:79]
	ds_read_b128 v[230:233], v250 offset:46112
	s_waitcnt lgkmcnt(6)
	v_mfma_f32_32x32x16_bf16 v[64:79], v[234:237], v[140:143], v[64:79]
	ds_read_b128 v[234:237], v250 offset:46144
	s_waitcnt lgkmcnt(6)
	v_mfma_f32_32x32x16_bf16 v[48:63], v[238:241], v[128:131], v[48:63]
	ds_read_b128 v[238:241], v250 offset:46176
	s_waitcnt lgkmcnt(6)
	v_mfma_f32_32x32x16_bf16 v[48:63], v[242:245], v[132:135], v[48:63]
	ds_read_b128 v[242:245], v250 offset:50688
	s_waitcnt lgkmcnt(6)
	v_mfma_f32_32x32x16_bf16 v[48:63], v[246:249], v[136:139], v[48:63]
	ds_read_b128 v[246:249], v250 offset:50720
	s_waitcnt lgkmcnt(6)
	v_mfma_f32_32x32x16_bf16 v[48:63], v[222:225], v[140:143], v[48:63]
	ds_read_b128 v[222:225], v250 offset:50752
	s_waitcnt lgkmcnt(6)
	v_mfma_f32_32x32x16_bf16 v[32:47], v[226:229], v[128:131], v[32:47]
	ds_read_b128 v[226:229], v250 offset:50784
	s_waitcnt lgkmcnt(6)
	v_mfma_f32_32x32x16_bf16 v[32:47], v[230:233], v[132:135], v[32:47]
	s_waitcnt lgkmcnt(5)
	v_mfma_f32_32x32x16_bf16 v[32:47], v[234:237], v[136:139], v[32:47]
	s_waitcnt lgkmcnt(4)
	v_mfma_f32_32x32x16_bf16 v[32:47], v[238:241], v[140:143], v[32:47]
	s_waitcnt lgkmcnt(3)
	v_mfma_f32_32x32x16_bf16 v[16:31], v[242:245], v[128:131], v[16:31]
	s_waitcnt lgkmcnt(2)
	v_mfma_f32_32x32x16_bf16 v[16:31], v[246:249], v[132:135], v[16:31]
	s_waitcnt lgkmcnt(1)
	v_mfma_f32_32x32x16_bf16 v[16:31], v[222:225], v[136:139], v[16:31]
	s_waitcnt lgkmcnt(0)
	v_mfma_f32_32x32x16_bf16 v[16:31], v[226:229], v[140:143], v[16:31]
	s_setprio 0
	s_andn2_b64 vcc, exec, s[24:25]
	s_cbranch_vccnz .LBB0_625
	s_sub_i32 s13, s10, 64
	v_cvt_f32_u32_e32 v2, s13
	v_mov_b32_e32 v0, v191
	s_cmp_gt_u32 s10, s38
	s_mov_b64 s[24:25], -1
	v_sub_f32_e32 v2, v221, v2
	s_cbranch_scc1 .LBB0_619
	v_fma_f32 v111, v2, -v0, -v195
	v_fma_f32 v80, 0, v0, v111
	v_fmamk_f32 v96, v0, 0x42000000, v111
	v_add_f32_e32 v81, v0, v111
	v_fmamk_f32 v97, v0, 0x42040000, v111
	v_fma_f32 v82, 2.0, v0, v111
	v_fmamk_f32 v98, v0, 0x42080000, v111
	v_fmamk_f32 v83, v0, 0x40400000, v111
	v_fmamk_f32 v99, v0, 0x420c0000, v111
	v_fmamk_f32 v84, v0, 0x41000000, v111
	v_fmamk_f32 v100, v0, 0x42200000, v111
	v_fmamk_f32 v85, v0, 0x41100000, v111
	v_fmamk_f32 v101, v0, 0x42240000, v111
	v_fmamk_f32 v86, v0, 0x41200000, v111
	v_fmamk_f32 v102, v0, 0x42280000, v111
	v_fmamk_f32 v87, v0, 0x41300000, v111
	v_fmamk_f32 v103, v0, 0x422c0000, v111
	v_fmamk_f32 v88, v0, 0x41800000, v111
	v_fmamk_f32 v104, v0, 0x42400000, v111
	v_fmamk_f32 v89, v0, 0x41880000, v111
	v_fmamk_f32 v105, v0, 0x42440000, v111
	v_fmamk_f32 v90, v0, 0x41900000, v111
	v_fmamk_f32 v106, v0, 0x42480000, v111
	v_fmamk_f32 v91, v0, 0x41980000, v111
	v_fmamk_f32 v107, v0, 0x424c0000, v111
	v_fmamk_f32 v92, v0, 0x41c00000, v111
	v_fmamk_f32 v108, v0, 0x42600000, v111
	v_fmamk_f32 v93, v0, 0x41c80000, v111
	v_fmamk_f32 v109, v0, 0x42640000, v111
	v_fmamk_f32 v94, v0, 0x41d00000, v111
	v_fmamk_f32 v110, v0, 0x42680000, v111
	v_fmamk_f32 v95, v0, 0x41d80000, v111
	v_fmac_f32_e32 v111, 0x426c0000, v0
	s_mov_b64 s[24:25], 0

.LBB0_624:
	s_bitcmp1_b32 s16, 0
	s_cselect_b32 s13, 0x4800, 0
	v_add_u32_e32 v0, s13, v215
	ds_read_b128 v[222:225], v0
	ds_read_b128 v[226:229], v0 offset:4608
	ds_read_b128 v[230:233], v0 offset:32
	ds_read_b128 v[234:237], v0 offset:4640
	ds_read_b128 v[238:241], v0 offset:64
	ds_read_b128 v[242:245], v0 offset:4672
	ds_read_b128 v[246:249], v0 offset:96
	s_waitcnt lgkmcnt(6)
	v_mfma_f32_32x32x16_bf16 v[80:95], v[222:225], v[112:115], v[80:95]
	ds_read_b128 v[222:225], v0 offset:4704
	s_waitcnt lgkmcnt(6)
	v_mfma_f32_32x32x16_bf16 v[96:111], v[226:229], v[112:115], v[96:111]
	s_waitcnt lgkmcnt(5)
	v_mfma_f32_32x32x16_bf16 v[80:95], v[230:233], v[116:119], v[80:95]
	s_waitcnt lgkmcnt(4)
	v_mfma_f32_32x32x16_bf16 v[96:111], v[234:237], v[116:119], v[96:111]
	s_waitcnt lgkmcnt(3)
	v_mfma_f32_32x32x16_bf16 v[80:95], v[238:241], v[120:123], v[80:95]
	s_waitcnt lgkmcnt(2)
	v_mfma_f32_32x32x16_bf16 v[96:111], v[242:245], v[120:123], v[96:111]
	s_waitcnt lgkmcnt(1)
	v_mfma_f32_32x32x16_bf16 v[80:95], v[246:249], v[124:127], v[80:95]
	s_waitcnt lgkmcnt(0)
	v_mfma_f32_32x32x16_bf16 v[96:111], v[222:225], v[124:127], v[96:111]
